# grid barrier: globally-last XCD leader bumps all 16 per-XCD XGEN release flags with one 16-lane atomic; other leaders wait on their own XGEN; TOPGEN hop and per-leader XGEN forward removed
# baseline (speedup 1.0000x reference)
.LBB0_135:
	s_or_b64 exec, exec, s[12:13]
	v_cvt_f32_u32_e32 v3, v0
	s_waitcnt vmcnt(0)
	v_readfirstlane_b32 s3, v2
	s_add_u32 s12, s8, 0x2400
	s_addc_u32 s13, s9, 0
	v_rcp_iflag_f32_e32 v3, v3
	v_add_u32_e32 v1, s3, v1
	v_add_u32_e32 v4, 1, v1
	s_mov_b64 s[14:15], 0
	v_mul_f32_e32 v2, 0x4f7ffffe, v3
	v_cvt_u32_f32_e32 v2, v2
	v_sub_u32_e32 v3, 0, v0
	v_mul_lo_u32 v3, v3, v2
	v_mul_hi_u32 v3, v2, v3
	v_add_u32_e32 v2, v2, v3
	v_mul_hi_u32 v2, v1, v2
	v_mul_lo_u32 v3, v2, v0
	v_sub_u32_e32 v1, v1, v3
	v_add_u32_e32 v5, 1, v2
	v_cmp_ge_u32_e32 vcc, v1, v0
	v_sub_u32_e32 v3, v1, v0
	s_nop 0
	v_cndmask_b32_e32 v2, v2, v5, vcc
	v_cndmask_b32_e32 v1, v1, v3, vcc
	v_add_u32_e32 v3, 1, v2
	v_cmp_ge_u32_e32 vcc, v1, v0
	s_nop 1
	v_cndmask_b32_e32 v2, v2, v3, vcc
	v_mul_lo_u32 v1, v0, v2
	v_add_u32_e32 v0, v1, v0
	v_cmp_ne_u32_e32 vcc, v4, v0
	v_mov_b64_e32 v[0:1], s[12:13]
	s_cbranch_vccnz .Lxb_nl_0
	s_mov_b64 exec, 0xffff
	v_mbcnt_lo_u32_b32 v7, -1, 0
	v_lshlrev_b32_e32 v7, 8, v7
	v_add_u32_e32 v7, 0x2400, v7
	v_mov_b32_e32 v8, 1
	global_atomic_add v7, v8, s[24:25]
	s_mov_b64 exec, 1
.Lxb_nl_0:
	s_and_saveexec_b64 s[10:11], vcc
	s_cbranch_execz .LBB0_147
	v_mov_b32_e32 v0, 0
	global_load_dword v1, v0, s[12:13] sc1
	s_mov_b64 s[18:19], 0
	s_waitcnt vmcnt(0)
	v_cmp_eq_u32_e32 vcc, v1, v2
	s_and_saveexec_b64 s[16:17], vcc
	s_cbranch_execz .LBB0_146
	s_add_u32 s14, s22, 0x80200
	s_addc_u32 s15, s23, 0
	s_mov_b32 s3, 1
	s_branch .LBB0_139

.LBB0_149:
	s_or_b64 exec, exec, s[10:11]
	s_mov_b64 s[10:11], exec
	v_mbcnt_lo_u32_b32 v0, s10, 0
	v_mbcnt_hi_u32_b32 v0, s11, v0
	v_cmp_eq_u32_e32 vcc, 0, v0
	s_waitcnt vmcnt(0)
	buffer_inv sc1
	s_and_saveexec_b64 s[12:13], vcc
	s_cbranch_execz .LBB0_151
	s_bcnt1_i32_b64 s3, s[10:11]
	v_mov_b32_e32 v0, 0x2000
	v_mov_b32_e32 v1, s3
.LBB0_151:
	s_or_b64 exec, exec, s[12:13]
	s_waitcnt vmcnt(0)

.LBB0_197:
	s_or_b64 exec, exec, s[16:17]
	v_cvt_f32_u32_e32 v3, v0
	s_waitcnt vmcnt(0)
	v_readfirstlane_b32 s3, v2
	s_add_u32 s16, s10, 0x2400
	s_addc_u32 s17, s11, 0
	v_rcp_iflag_f32_e32 v3, v3
	v_add_u32_e32 v1, s3, v1
	v_add_u32_e32 v4, 1, v1
	s_mov_b64 s[18:19], 0
	v_mul_f32_e32 v2, 0x4f7ffffe, v3
	v_cvt_u32_f32_e32 v2, v2
	v_sub_u32_e32 v3, 0, v0
	v_mul_lo_u32 v3, v3, v2
	v_mul_hi_u32 v3, v2, v3
	v_add_u32_e32 v2, v2, v3
	v_mul_hi_u32 v2, v1, v2
	v_mul_lo_u32 v3, v2, v0
	v_sub_u32_e32 v1, v1, v3
	v_add_u32_e32 v5, 1, v2
	v_cmp_ge_u32_e32 vcc, v1, v0
	v_sub_u32_e32 v3, v1, v0
	s_nop 0
	v_cndmask_b32_e32 v2, v2, v5, vcc
	v_cndmask_b32_e32 v1, v1, v3, vcc
	v_add_u32_e32 v3, 1, v2
	v_cmp_ge_u32_e32 vcc, v1, v0
	s_nop 1
	v_cndmask_b32_e32 v2, v2, v3, vcc
	v_mul_lo_u32 v1, v0, v2
	v_add_u32_e32 v0, v1, v0
	v_cmp_ne_u32_e32 vcc, v4, v0
	v_mov_b64_e32 v[0:1], s[16:17]
	s_cbranch_vccnz .Lxb_nl_1
	s_mov_b64 exec, 0xffff
	v_mbcnt_lo_u32_b32 v7, -1, 0
	v_lshlrev_b32_e32 v7, 8, v7
	v_add_u32_e32 v7, 0x2400, v7
	v_mov_b32_e32 v8, 1
	global_atomic_add v7, v8, s[24:25]
	s_mov_b64 exec, 1
.Lxb_nl_1:
	s_and_saveexec_b64 s[14:15], vcc
	s_cbranch_execz .LBB0_209
	v_mov_b32_e32 v0, 0
	global_load_dword v1, v0, s[16:17] sc1
	s_mov_b64 s[26:27], 0
	s_waitcnt vmcnt(0)
	v_cmp_eq_u32_e32 vcc, v1, v2
	s_and_saveexec_b64 s[20:21], vcc
	s_cbranch_execz .LBB0_208
	s_add_u32 s18, s22, 0x80200
	s_addc_u32 s19, s23, 0
	s_mov_b32 s3, 1
	s_branch .LBB0_201

.LBB0_211:
	s_or_b64 exec, exec, s[14:15]
	s_mov_b64 s[14:15], exec
	v_mbcnt_lo_u32_b32 v0, s14, 0
	v_mbcnt_hi_u32_b32 v0, s15, v0
	v_cmp_eq_u32_e32 vcc, 0, v0
	s_waitcnt vmcnt(0)
	buffer_inv sc1
	s_and_saveexec_b64 s[16:17], vcc
	s_cbranch_execz .LBB0_213
	s_bcnt1_i32_b64 s3, s[14:15]
	v_mov_b32_e32 v0, 0x2000
	v_mov_b32_e32 v1, s3
.LBB0_213:
	s_or_b64 exec, exec, s[16:17]
	s_waitcnt vmcnt(0)

.LBB0_368:
	s_or_b64 exec, exec, s[14:15]
	s_mov_b64 s[14:15], exec
	v_mbcnt_lo_u32_b32 v0, s14, 0
	v_mbcnt_hi_u32_b32 v0, s15, v0
	v_cmp_eq_u32_e32 vcc, 0, v0
	s_waitcnt vmcnt(0)
	buffer_inv sc1
	s_and_saveexec_b64 s[16:17], vcc
	s_cbranch_execz .LBB0_370
	s_bcnt1_i32_b64 s3, s[14:15]
	v_mov_b32_e32 v0, 0x2000
	v_mov_b32_e32 v1, s3
.LBB0_370:
	s_or_b64 exec, exec, s[16:17]
	s_waitcnt vmcnt(0)

.LBB0_471:
	s_or_b64 exec, exec, s[16:17]
	v_cvt_f32_u32_e32 v3, v0
	s_waitcnt vmcnt(0)
	v_readfirstlane_b32 s3, v2
	s_add_u32 s16, s12, 0x2400
	s_addc_u32 s17, s13, 0
	v_rcp_iflag_f32_e32 v3, v3
	v_add_u32_e32 v1, s3, v1
	v_add_u32_e32 v4, 1, v1
	s_mov_b64 s[18:19], 0
	v_mul_f32_e32 v2, 0x4f7ffffe, v3
	v_cvt_u32_f32_e32 v2, v2
	v_sub_u32_e32 v3, 0, v0
	v_mul_lo_u32 v3, v3, v2
	v_mul_hi_u32 v3, v2, v3
	v_add_u32_e32 v2, v2, v3
	v_mul_hi_u32 v2, v1, v2
	v_mul_lo_u32 v3, v2, v0
	v_sub_u32_e32 v1, v1, v3
	v_add_u32_e32 v5, 1, v2
	v_cmp_ge_u32_e32 vcc, v1, v0
	v_sub_u32_e32 v3, v1, v0
	s_nop 0
	v_cndmask_b32_e32 v2, v2, v5, vcc
	v_cndmask_b32_e32 v1, v1, v3, vcc
	v_add_u32_e32 v3, 1, v2
	v_cmp_ge_u32_e32 vcc, v1, v0
	s_nop 1
	v_cndmask_b32_e32 v2, v2, v3, vcc
	v_mul_lo_u32 v1, v0, v2
	v_add_u32_e32 v0, v1, v0
	v_cmp_ne_u32_e32 vcc, v4, v0
	v_mov_b64_e32 v[0:1], s[16:17]
	s_cbranch_vccnz .Lxb_nl_3
	s_mov_b64 exec, 0xffff
	v_mbcnt_lo_u32_b32 v7, -1, 0
	v_lshlrev_b32_e32 v7, 8, v7
	v_add_u32_e32 v7, 0x2400, v7
	v_mov_b32_e32 v8, 1
	global_atomic_add v7, v8, s[24:25]
	s_mov_b64 exec, 1

.LBB0_485:
	s_or_b64 exec, exec, s[14:15]
	s_mov_b64 s[14:15], exec
	v_mbcnt_lo_u32_b32 v0, s14, 0
	v_mbcnt_hi_u32_b32 v0, s15, v0
	v_cmp_eq_u32_e32 vcc, 0, v0
	s_waitcnt vmcnt(0)
	buffer_inv sc1
	s_and_saveexec_b64 s[16:17], vcc
	s_cbranch_execz .LBB0_487
	s_bcnt1_i32_b64 s3, s[14:15]
	v_mov_b32_e32 v0, 0x2000
	v_mov_b32_e32 v1, s3
.LBB0_487:
	s_or_b64 exec, exec, s[16:17]
	s_waitcnt vmcnt(0)

.LBB0_550:
	s_or_b64 exec, exec, s[14:15]
	s_mov_b64 s[14:15], exec
	v_mbcnt_lo_u32_b32 v0, s14, 0
	v_mbcnt_hi_u32_b32 v0, s15, v0
	v_cmp_eq_u32_e32 vcc, 0, v0
	s_waitcnt vmcnt(0)
	buffer_inv sc1
	s_and_saveexec_b64 s[16:17], vcc
	s_cbranch_execz .LBB0_552
	s_bcnt1_i32_b64 s3, s[14:15]
	v_mov_b32_e32 v0, 0x2000
	v_mov_b32_e32 v1, s3
.LBB0_552:
	s_or_b64 exec, exec, s[16:17]
	s_waitcnt vmcnt(0)

.LBB0_618:
	s_or_b64 exec, exec, s[14:15]
	s_mov_b64 s[14:15], exec
	v_mbcnt_lo_u32_b32 v0, s14, 0
	v_mbcnt_hi_u32_b32 v0, s15, v0
	v_cmp_eq_u32_e32 vcc, 0, v0
	s_waitcnt vmcnt(0)
	buffer_inv sc1
	s_and_saveexec_b64 s[16:17], vcc
	s_cbranch_execz .LBB0_620
	s_bcnt1_i32_b64 s3, s[14:15]
	v_mov_b32_e32 v0, 0x2000
	v_mov_b32_e32 v1, s3
.LBB0_620:
	s_or_b64 exec, exec, s[16:17]
	s_waitcnt vmcnt(0)

.LBB0_684:
	s_or_b64 exec, exec, s[14:15]
	s_mov_b64 s[14:15], exec
	v_mbcnt_lo_u32_b32 v0, s14, 0
	v_mbcnt_hi_u32_b32 v0, s15, v0
	v_cmp_eq_u32_e32 vcc, 0, v0
	s_waitcnt vmcnt(0)
	buffer_inv sc1
	s_and_saveexec_b64 s[16:17], vcc
	s_cbranch_execz .LBB0_686
	s_bcnt1_i32_b64 s3, s[14:15]
	v_mov_b32_e32 v0, 0x2000
	v_mov_b32_e32 v1, s3
.LBB0_686:
	s_or_b64 exec, exec, s[16:17]
	s_waitcnt vmcnt(0)

.LBB0_732:
	s_or_b64 exec, exec, s[14:15]
	v_cvt_f32_u32_e32 v3, v0
	s_waitcnt vmcnt(0)
	v_readfirstlane_b32 s3, v2
	s_add_u32 s14, s10, 0x2400
	s_addc_u32 s15, s11, 0
	v_rcp_iflag_f32_e32 v3, v3
	v_add_u32_e32 v1, s3, v1
	v_add_u32_e32 v4, 1, v1
	s_mov_b64 s[18:19], 0
	v_mul_f32_e32 v2, 0x4f7ffffe, v3
	v_cvt_u32_f32_e32 v2, v2
	v_sub_u32_e32 v3, 0, v0
	v_mul_lo_u32 v3, v3, v2
	v_mul_hi_u32 v3, v2, v3
	v_add_u32_e32 v2, v2, v3
	v_mul_hi_u32 v2, v1, v2
	v_mul_lo_u32 v3, v2, v0
	v_sub_u32_e32 v1, v1, v3
	v_add_u32_e32 v5, 1, v2
	v_cmp_ge_u32_e32 vcc, v1, v0
	v_sub_u32_e32 v3, v1, v0
	s_nop 0
	v_cndmask_b32_e32 v2, v2, v5, vcc
	v_cndmask_b32_e32 v1, v1, v3, vcc
	v_add_u32_e32 v3, 1, v2
	v_cmp_ge_u32_e32 vcc, v1, v0
	s_nop 1
	v_cndmask_b32_e32 v2, v2, v3, vcc
	v_mul_lo_u32 v1, v0, v2
	v_add_u32_e32 v0, v1, v0
	v_cmp_ne_u32_e32 vcc, v4, v0
	v_mov_b64_e32 v[0:1], s[14:15]
	s_cbranch_vccnz .Lxb_nl_7
	s_mov_b64 exec, 0xffff
	v_mbcnt_lo_u32_b32 v7, -1, 0
	v_lshlrev_b32_e32 v7, 8, v7
	v_add_u32_e32 v7, 0x2400, v7
	v_mov_b32_e32 v8, 1
	global_atomic_add v7, v8, s[24:25]
	s_mov_b64 exec, 1
.Lxb_nl_7:
	s_and_saveexec_b64 s[12:13], vcc
	s_cbranch_execz .LBB0_744
	v_mov_b32_e32 v0, 0
	global_load_dword v1, v0, s[14:15] sc1
	s_mov_b64 s[26:27], 0
	s_waitcnt vmcnt(0)
	v_cmp_eq_u32_e32 vcc, v1, v2
	s_and_saveexec_b64 s[20:21], vcc
	s_cbranch_execz .LBB0_743
	s_add_u32 s18, s22, 0x80200
	s_addc_u32 s19, s23, 0
	s_mov_b32 s3, 1
	s_branch .LBB0_736

.LBB0_746:
	s_or_b64 exec, exec, s[12:13]
	s_mov_b64 s[12:13], exec
	v_mbcnt_lo_u32_b32 v0, s12, 0
	v_mbcnt_hi_u32_b32 v0, s13, v0
	v_cmp_eq_u32_e32 vcc, 0, v0
	s_waitcnt vmcnt(0)
	buffer_inv sc1
	s_and_saveexec_b64 s[14:15], vcc
	s_cbranch_execz .LBB0_748
	s_bcnt1_i32_b64 s3, s[12:13]
	v_mov_b32_e32 v0, 0x2000
	v_mov_b32_e32 v1, s3
.LBB0_748:
	s_or_b64 exec, exec, s[14:15]
	s_waitcnt vmcnt(0)

.LBB0_806:
	s_or_b64 exec, exec, s[14:15]
	s_mov_b64 s[14:15], exec
	v_mbcnt_lo_u32_b32 v0, s14, 0
	v_mbcnt_hi_u32_b32 v0, s15, v0
	v_cmp_eq_u32_e32 vcc, 0, v0
	s_waitcnt vmcnt(0)
	buffer_inv sc1
	s_and_saveexec_b64 s[16:17], vcc
	s_cbranch_execz .LBB0_808
	s_bcnt1_i32_b64 s3, s[14:15]
	v_mov_b32_e32 v0, 0x2000
	v_mov_b32_e32 v1, s3
.LBB0_808:
	s_or_b64 exec, exec, s[16:17]
	s_waitcnt vmcnt(0)

.LBB0_882:
	s_or_b64 exec, exec, s[16:17]
	v_cvt_f32_u32_e32 v3, v0
	s_waitcnt vmcnt(0)
	v_readfirstlane_b32 s3, v2
	s_add_u32 s16, s8, 0x2400
	s_addc_u32 s17, s9, 0
	v_rcp_iflag_f32_e32 v3, v3
	v_add_u32_e32 v1, s3, v1
	v_add_u32_e32 v4, 1, v1
	s_mov_b64 s[18:19], 0
	v_mul_f32_e32 v2, 0x4f7ffffe, v3
	v_cvt_u32_f32_e32 v2, v2
	v_sub_u32_e32 v3, 0, v0
	v_mul_lo_u32 v3, v3, v2
	v_mul_hi_u32 v3, v2, v3
	v_add_u32_e32 v2, v2, v3
	v_mul_hi_u32 v2, v1, v2
	v_mul_lo_u32 v3, v2, v0
	v_sub_u32_e32 v1, v1, v3
	v_add_u32_e32 v5, 1, v2
	v_cmp_ge_u32_e32 vcc, v1, v0
	v_sub_u32_e32 v3, v1, v0
	s_nop 0
	v_cndmask_b32_e32 v2, v2, v5, vcc
	v_cndmask_b32_e32 v1, v1, v3, vcc
	v_add_u32_e32 v3, 1, v2
	v_cmp_ge_u32_e32 vcc, v1, v0
	s_nop 1
	v_cndmask_b32_e32 v2, v2, v3, vcc
	v_mul_lo_u32 v1, v0, v2
	v_add_u32_e32 v0, v1, v0
	v_cmp_ne_u32_e32 vcc, v4, v0
	v_mov_b64_e32 v[0:1], s[16:17]
	s_cbranch_vccnz .Lxb_nl_9
	s_mov_b64 exec, 0xffff
	v_mbcnt_lo_u32_b32 v7, -1, 0
	v_lshlrev_b32_e32 v7, 8, v7
	v_add_u32_e32 v7, 0x2400, v7
	v_mov_b32_e32 v8, 1
	global_atomic_add v7, v8, s[24:25]
	s_mov_b64 exec, 1

.LBB0_896:
	s_or_b64 exec, exec, s[14:15]
	s_mov_b64 s[14:15], exec
	v_mbcnt_lo_u32_b32 v0, s14, 0
	v_mbcnt_hi_u32_b32 v0, s15, v0
	v_cmp_eq_u32_e32 vcc, 0, v0
	s_waitcnt vmcnt(0)
	buffer_inv sc1
	s_and_saveexec_b64 s[16:17], vcc
	s_cbranch_execz .LBB0_898
	s_bcnt1_i32_b64 s3, s[14:15]
	v_mov_b32_e32 v0, 0x2000
	v_mov_b32_e32 v1, s3
.LBB0_898:
	s_or_b64 exec, exec, s[16:17]
	s_waitcnt vmcnt(0)

.LBB0_1078:
	s_or_b64 exec, exec, s[14:15]
	v_cvt_f32_u32_e32 v3, v0
	s_waitcnt vmcnt(0)
	v_readfirstlane_b32 s3, v2
	s_add_u32 s14, s8, 0x2400
	s_addc_u32 s15, s9, 0
	v_rcp_iflag_f32_e32 v3, v3
	v_add_u32_e32 v1, s3, v1
	v_add_u32_e32 v4, 1, v1
	s_mov_b64 s[16:17], 0
	v_mul_f32_e32 v2, 0x4f7ffffe, v3
	v_cvt_u32_f32_e32 v2, v2
	v_sub_u32_e32 v3, 0, v0
	v_mul_lo_u32 v3, v3, v2
	v_mul_hi_u32 v3, v2, v3
	v_add_u32_e32 v2, v2, v3
	v_mul_hi_u32 v2, v1, v2
	v_mul_lo_u32 v3, v2, v0
	v_sub_u32_e32 v1, v1, v3
	v_add_u32_e32 v5, 1, v2
	v_cmp_ge_u32_e32 vcc, v1, v0
	v_sub_u32_e32 v3, v1, v0
	s_nop 0
	v_cndmask_b32_e32 v2, v2, v5, vcc
	v_cndmask_b32_e32 v1, v1, v3, vcc
	v_add_u32_e32 v3, 1, v2
	v_cmp_ge_u32_e32 vcc, v1, v0
	s_nop 1
	v_cndmask_b32_e32 v2, v2, v3, vcc
	v_mul_lo_u32 v1, v0, v2
	v_add_u32_e32 v0, v1, v0
	v_cmp_ne_u32_e32 vcc, v4, v0
	v_mov_b64_e32 v[0:1], s[14:15]
	s_cbranch_vccnz .Lxb_nl_10
	s_mov_b64 exec, 0xffff
	v_mbcnt_lo_u32_b32 v7, -1, 0
	v_lshlrev_b32_e32 v7, 8, v7
	v_add_u32_e32 v7, 0x2400, v7
	v_mov_b32_e32 v8, 1
	global_atomic_add v7, v8, s[24:25]
	s_mov_b64 exec, 1
.Lxb_nl_10:
	s_and_saveexec_b64 s[10:11], vcc
	s_cbranch_execz .LBB0_1090
	v_mov_b32_e32 v0, 0
	global_load_dword v1, v0, s[14:15] sc1
	s_mov_b64 s[20:21], 0
	s_waitcnt vmcnt(0)
	v_cmp_eq_u32_e32 vcc, v1, v2
	s_and_saveexec_b64 s[18:19], vcc
	s_cbranch_execz .LBB0_1089
	s_add_u32 s16, s22, 0x80200
	s_addc_u32 s17, s23, 0
	s_mov_b32 s3, 1
	s_branch .LBB0_1082

.LBB0_1092:
	s_or_b64 exec, exec, s[10:11]
	s_mov_b64 s[10:11], exec
	v_mbcnt_lo_u32_b32 v0, s10, 0
	v_mbcnt_hi_u32_b32 v0, s11, v0
	v_cmp_eq_u32_e32 vcc, 0, v0
	s_waitcnt vmcnt(0)
	buffer_inv sc1
	s_and_saveexec_b64 s[14:15], vcc
	s_cbranch_execz .LBB0_1094
	s_bcnt1_i32_b64 s3, s[10:11]
	v_mov_b32_e32 v0, 0x2000
	v_mov_b32_e32 v1, s3
.LBB0_1094:
	s_or_b64 exec, exec, s[14:15]
	s_waitcnt vmcnt(0)

.LBB0_1383:
	s_or_b64 exec, exec, s[14:15]
	v_cvt_f32_u32_e32 v3, v0
	s_waitcnt vmcnt(0)
	v_readfirstlane_b32 s3, v2
	s_add_u32 s14, s10, 0x2400
	s_addc_u32 s15, s11, 0
	v_rcp_iflag_f32_e32 v3, v3
	v_add_u32_e32 v1, s3, v1
	v_add_u32_e32 v4, 1, v1
	s_mov_b64 s[16:17], 0
	v_mul_f32_e32 v2, 0x4f7ffffe, v3
	v_cvt_u32_f32_e32 v2, v2
	v_sub_u32_e32 v3, 0, v0
	v_mul_lo_u32 v3, v3, v2
	v_mul_hi_u32 v3, v2, v3
	v_add_u32_e32 v2, v2, v3
	v_mul_hi_u32 v2, v1, v2
	v_mul_lo_u32 v3, v2, v0
	v_sub_u32_e32 v1, v1, v3
	v_add_u32_e32 v5, 1, v2
	v_cmp_ge_u32_e32 vcc, v1, v0
	v_sub_u32_e32 v3, v1, v0
	s_nop 0
	v_cndmask_b32_e32 v2, v2, v5, vcc
	v_cndmask_b32_e32 v1, v1, v3, vcc
	v_add_u32_e32 v3, 1, v2
	v_cmp_ge_u32_e32 vcc, v1, v0
	s_nop 1
	v_cndmask_b32_e32 v2, v2, v3, vcc
	v_mul_lo_u32 v1, v0, v2
	v_add_u32_e32 v0, v1, v0
	v_cmp_ne_u32_e32 vcc, v4, v0
	v_mov_b64_e32 v[0:1], s[14:15]
	s_cbranch_vccnz .Lxb_nl_11
	s_mov_b64 exec, 0xffff
	v_mbcnt_lo_u32_b32 v7, -1, 0
	v_lshlrev_b32_e32 v7, 8, v7
	v_add_u32_e32 v7, 0x2400, v7
	v_mov_b32_e32 v8, 1
	global_atomic_add v7, v8, s[24:25]
	s_mov_b64 exec, 1
.Lxb_nl_11:
	s_and_saveexec_b64 s[12:13], vcc
	s_cbranch_execz .LBB0_1395
	v_mov_b32_e32 v0, 0
	global_load_dword v1, v0, s[14:15] sc1
	s_mov_b64 s[26:27], 0
	s_waitcnt vmcnt(0)
	v_cmp_eq_u32_e32 vcc, v1, v2
	s_and_saveexec_b64 s[18:19], vcc
	s_cbranch_execz .LBB0_1394
	s_add_u32 s16, s22, 0x80200
	s_addc_u32 s17, s23, 0
	s_mov_b32 s3, 1
	s_branch .LBB0_1387

.LBB0_1397:
	s_or_b64 exec, exec, s[12:13]
	s_mov_b64 s[12:13], exec
	v_mbcnt_lo_u32_b32 v0, s12, 0
	v_mbcnt_hi_u32_b32 v0, s13, v0
	v_cmp_eq_u32_e32 vcc, 0, v0
	s_waitcnt vmcnt(0)
	buffer_inv sc1
	s_and_saveexec_b64 s[14:15], vcc
	s_cbranch_execz .LBB0_1399
	s_bcnt1_i32_b64 s3, s[12:13]
	v_mov_b32_e32 v0, 0x2000
	v_mov_b32_e32 v1, s3
.LBB0_1399:
	s_or_b64 exec, exec, s[14:15]
	s_waitcnt vmcnt(0)

.LBB0_1457:
	s_or_b64 exec, exec, s[14:15]
	s_mov_b64 s[14:15], exec
	v_mbcnt_lo_u32_b32 v0, s14, 0
	v_mbcnt_hi_u32_b32 v0, s15, v0
	v_cmp_eq_u32_e32 vcc, 0, v0
	s_waitcnt vmcnt(0)
	buffer_inv sc1
	s_and_saveexec_b64 s[16:17], vcc
	s_cbranch_execz .LBB0_1459
	s_bcnt1_i32_b64 s3, s[14:15]
	v_mov_b32_e32 v0, 0x2000
	v_mov_b32_e32 v1, s3
.LBB0_1459:
	s_or_b64 exec, exec, s[16:17]
	s_waitcnt vmcnt(0)

.LBB0_1519:
	s_or_b64 exec, exec, s[14:15]
	s_mov_b64 s[14:15], exec
	v_mbcnt_lo_u32_b32 v0, s14, 0
	v_mbcnt_hi_u32_b32 v0, s15, v0
	v_cmp_eq_u32_e32 vcc, 0, v0
	s_waitcnt vmcnt(0)
	buffer_inv sc1
	s_and_saveexec_b64 s[16:17], vcc
	s_cbranch_execz .LBB0_1521
	s_bcnt1_i32_b64 s3, s[14:15]
	v_mov_b32_e32 v0, 0x2000
	v_mov_b32_e32 v1, s3
.LBB0_1521:
	s_or_b64 exec, exec, s[16:17]
	s_waitcnt vmcnt(0)

.LBB0_1567:
	s_or_b64 exec, exec, s[4:5]
	v_cvt_f32_u32_e32 v3, v0
	s_waitcnt vmcnt(0)
	v_readfirstlane_b32 s2, v2
	s_add_u32 s4, s0, 0x2400
	s_addc_u32 s5, s1, 0
	v_rcp_iflag_f32_e32 v3, v3
	v_add_u32_e32 v1, s2, v1
	v_add_u32_e32 v4, 1, v1
	s_mov_b64 s[6:7], 0
	v_mul_f32_e32 v2, 0x4f7ffffe, v3
	v_cvt_u32_f32_e32 v2, v2
	v_sub_u32_e32 v3, 0, v0
	v_mul_lo_u32 v3, v3, v2
	v_mul_hi_u32 v3, v2, v3
	v_add_u32_e32 v2, v2, v3
	v_mul_hi_u32 v2, v1, v2
	v_mul_lo_u32 v3, v2, v0
	v_sub_u32_e32 v1, v1, v3
	v_add_u32_e32 v5, 1, v2
	v_cmp_ge_u32_e32 vcc, v1, v0
	v_sub_u32_e32 v3, v1, v0
	s_nop 0
	v_cndmask_b32_e32 v2, v2, v5, vcc
	v_cndmask_b32_e32 v1, v1, v3, vcc
	v_add_u32_e32 v3, 1, v2
	v_cmp_ge_u32_e32 vcc, v1, v0
	s_nop 1
	v_cndmask_b32_e32 v2, v2, v3, vcc
	v_mul_lo_u32 v1, v0, v2
	v_add_u32_e32 v0, v1, v0
	v_cmp_ne_u32_e32 vcc, v4, v0
	v_mov_b64_e32 v[0:1], s[4:5]
	s_cbranch_vccnz .Lxb_nl_14
	s_mov_b64 exec, 0xffff
	v_mbcnt_lo_u32_b32 v7, -1, 0
	v_lshlrev_b32_e32 v7, 8, v7
	v_add_u32_e32 v7, 0x2400, v7
	v_mov_b32_e32 v8, 1
	global_atomic_add v7, v8, s[24:25]
	s_mov_b64 exec, 1
.Lxb_nl_14:
	s_and_saveexec_b64 s[2:3], vcc
	s_cbranch_execz .LBB0_1579
	v_mov_b32_e32 v0, 0
	global_load_dword v1, v0, s[4:5] sc1
	s_mov_b64 s[10:11], 0
	s_waitcnt vmcnt(0)
	v_cmp_eq_u32_e32 vcc, v1, v2
	s_and_saveexec_b64 s[8:9], vcc
	s_cbranch_execz .LBB0_1578
	s_add_u32 s6, s22, 0x80200
	s_addc_u32 s7, s23, 0
	s_mov_b32 s20, 1
	s_branch .LBB0_1571

.LBB0_1581:
	s_or_b64 exec, exec, s[2:3]
	s_mov_b64 s[2:3], exec
	v_mbcnt_lo_u32_b32 v0, s2, 0
	v_mbcnt_hi_u32_b32 v0, s3, v0
	v_cmp_eq_u32_e32 vcc, 0, v0
	s_waitcnt vmcnt(0)
	buffer_inv sc1
	s_and_saveexec_b64 s[4:5], vcc
	s_cbranch_execz .LBB0_1583
	s_bcnt1_i32_b64 s2, s[2:3]
	v_mov_b32_e32 v0, 0x2000
	v_mov_b32_e32 v1, s2
.LBB0_1583:
	s_or_b64 exec, exec, s[4:5]
	s_waitcnt vmcnt(0)
